# P1: first K iteration peeled with SrcC=0 MFMAs, 128 accumulator clears per tile removed
# speedup vs baseline: 1.0154x; 1.0154x over previous
; #define PG8_STAGE(bufoff, gbase, voff) do { _Pragma("unroll") for (int _i = 0; _i < 2; ++_i) \
;         __builtin_amdgcn_global_load_lds((const unsigned*)((const char*)(gbase) + (voff)[_i]), (LAS unsigned*)(lds + (bufoff) + ldsw + _i * 8192), 16, 0, 0); } while (0)
; #define PG8_LDA(dst, b, h) do { _Pragma("unroll") for (int m = 0; m < 4; ++m) _Pragma("unroll") for (int k = 0; k < 2; ++k) dst[m][k] = *(const LAS bf16x8*)(lds + PG8_SA(b, h) + aoff + m * 2048 + k * 1024); } while (0)
; #define PG8_LDB(dst, b, h) do { _Pragma("unroll") for (int n = 0; n < 2; ++n) _Pragma("unroll") for (int k = 0; k < 2; ++k) dst[n][k] = *(const LAS bf16x8*)(lds + PG8_SB(b, h) + boff + n * 2048 + k * 1024); } while (0)
; #define PG8_WAIT_V(n) asm volatile("s_waitcnt vmcnt(" #n ")" ::: "memory")
; #define PG8_WAIT_L(n) asm volatile("s_waitcnt lgkmcnt(" #n ")" ::: "memory")
; #define PG8_BAR __builtin_amdgcn_s_barrier()
; #define PG8_SCHED __builtin_amdgcn_sched_barrier(0)
; template <class Epi, class Sched>
; __device__ __forceinline__ void gemm_phase(LAS unsigned char* lds, const Gemm g, const Sched& S, const Epi& E) {
;     ...
;     for (;;) {
;         const bool has_next = S.next(ui + 1, nxt);
;         const char* nA = has_next ? (const char*)g.A + (size_t)nxt.b * g.abs * 2 + (size_t)nxt.pm * tstepA : cA;
;         const char* nB = has_next ? (const char*)g.Bt + (size_t)nxt.b * g.bbs * 2 + (size_t)nxt.pn * tstepB : cB;
;         for (int t = 0; t < nt; t += 2) {
;             const bool last = (t == nt - 2);
;             const char* a1 = cA + (size_t)(t + 1) * kstep;
;             const char* a2 = last ? nA : cA + (size_t)(t + 2) * kstep; const char* b2 = last ? nB : cB + (size_t)(t + 2) * kstep;
;             const char* a3 = a2 + kstep; const char* b3 = b2 + kstep;
;             PG8_LDB(B0, 0, 0); PG8_LDB(B1, 0, 1); PG8_SCHED; PG8_LDA(At, 0, 0); PG8_STAGE(PG8_SA(1, 1), a1 + hstepA, voffA);
;             PG8_WAIT_V(8); PG8_WAIT_L(0); PG8_BAR; PG8_MMA(0, 0, At, B0); PG8_MMA(0, 1, At, B1); PG8_BAR; PG8_SCHED;
;             PG8_LDA(At, 0, 1); PG8_STAGE(PG8_SB(0, 0), b2, voffB); PG8_STAGE(PG8_SB(0, 1), b2 + hstepB, voffB); PG8_STAGE(PG8_SA(0, 0), a2, voffA);
;             PG8_WAIT_V(8); PG8_WAIT_L(0); PG8_BAR; PG8_MMA(1, 0, At, B0); PG8_MMA(1, 1, At, B1); PG8_BAR; PG8_SCHED;
.LBB0_279:
	s_ashr_i32 s19, s18, 31
	s_lshl_b64 s[14:15], s[18:19], 19
	s_add_u32 s20, s92, s14
	s_addc_u32 s21, s93, s15
	s_and_b64 s[14:15], s[40:41], exec
	s_cselect_b32 s6, s21, s25
	s_cselect_b32 s14, s20, s24
	s_ashr_i32 s17, s16, 31
	s_lshl_b64 s[22:23], s[16:17], 19
	v_readlane_b32 s36, v254, 62
	v_readlane_b32 s37, v254, 63
	s_add_u32 s22, s36, s22
	s_addc_u32 s23, s37, s23
	s_and_b64 s[36:37], s[40:41], exec
	s_cselect_b32 s15, s23, s27
	s_cselect_b32 s17, s22, s26
	s_add_u32 s24, s24, 0x40080
	s_addc_u32 s25, s25, 0
	s_add_u32 s19, s26, 0x100
	s_addc_u32 s42, s27, 0
	s_mov_b32 s43, -2
	s_waitcnt lgkmcnt(0)
	s_cmp_eq_u32 s61, 0
	s_cbranch_scc1 .Lp1_nobar
	s_mov_b32 s61, 0
	s_barrier
.Lp1_nobar:
	s_add_u32 s26, s24, 0xfffc0080
	s_addc_u32 s27, s25, -1
	s_add_i32 s44, 0, 0x10000
	s_cmp_eq_u32 s43, 12
	s_cselect_b32 s37, s6, s27
	s_cselect_b32 s36, s14, s26
	v_add_u32_e32 v145, s44, v165
	s_cselect_b32 s27, s15, s42
	s_cselect_b32 s26, s17, s19
	s_add_i32 s46, 0, 0x14000
	ds_read_b128 v[148:151], v145
	ds_read_b128 v[152:155], v145 offset:1024
	ds_read_b128 v[156:159], v145 offset:2048
	ds_read_b128 v[160:163], v145 offset:3072
	v_add_u32_e32 v145, s46, v165
	ds_read_b128 v[168:171], v145
	ds_read_b128 v[172:175], v145 offset:1024
	ds_read_b128 v[176:179], v145 offset:2048
	ds_read_b128 v[180:183], v145 offset:3072
	s_add_i32 m0, s52, 0xc000
	ds_read_b128 v[184:187], v167
	ds_read_b128 v[188:191], v167 offset:1024
	ds_read_b128 v[192:195], v167 offset:2048
	ds_read_b128 v[196:199], v167 offset:3072
	ds_read_b128 v[200:203], v167 offset:4096
	ds_read_b128 v[204:207], v167 offset:5120
	ds_read_b128 v[208:211], v167 offset:6144
	ds_read_b128 v[214:217], v167 offset:7168
	global_load_lds_dwordx4 v140, s[24:25]
	s_add_i32 m0, s52, 0xe000
	s_nop 0
	global_load_lds_dwordx4 v142, s[24:25]
	s_waitcnt vmcnt(8)
	s_waitcnt lgkmcnt(0)
	s_barrier
	s_setprio 1
	s_waitcnt lgkmcnt(0)
	v_mfma_f32_16x16x32_bf16 v[124:127], v[148:151], v[184:187], 0
	v_mfma_f32_16x16x32_bf16 v[120:123], v[156:159], v[184:187], 0
	v_mfma_f32_16x16x32_bf16 v[108:111], v[148:151], v[192:195], 0
	v_mfma_f32_16x16x32_bf16 v[104:107], v[156:159], v[192:195], 0
	v_mfma_f32_16x16x32_bf16 v[92:95], v[148:151], v[200:203], 0
	v_mfma_f32_16x16x32_bf16 v[88:91], v[156:159], v[200:203], 0
	v_mfma_f32_16x16x32_bf16 v[76:79], v[148:151], v[208:211], 0
	v_mfma_f32_16x16x32_bf16 v[72:75], v[156:159], v[208:211], 0
	v_mfma_f32_16x16x32_bf16 v[124:127], v[152:155], v[188:191], v[124:127]
	v_mfma_f32_16x16x32_bf16 v[120:123], v[160:163], v[188:191], v[120:123]
	v_mfma_f32_16x16x32_bf16 v[108:111], v[152:155], v[196:199], v[108:111]
	v_mfma_f32_16x16x32_bf16 v[104:107], v[160:163], v[196:199], v[104:107]
	v_mfma_f32_16x16x32_bf16 v[92:95], v[152:155], v[204:207], v[92:95]
	v_mfma_f32_16x16x32_bf16 v[88:91], v[160:163], v[204:207], v[88:91]
	v_mfma_f32_16x16x32_bf16 v[76:79], v[152:155], v[214:217], v[76:79]
	v_mfma_f32_16x16x32_bf16 v[72:75], v[160:163], v[214:217], v[72:75]
	s_setprio 0
	s_setprio 1
	v_mfma_f32_16x16x32_bf16 v[116:119], v[168:171], v[184:187], 0
	v_mfma_f32_16x16x32_bf16 v[112:115], v[176:179], v[184:187], 0
	v_mfma_f32_16x16x32_bf16 v[100:103], v[168:171], v[192:195], 0
	v_mfma_f32_16x16x32_bf16 v[96:99], v[176:179], v[192:195], 0
	v_mfma_f32_16x16x32_bf16 v[84:87], v[168:171], v[200:203], 0
	v_mfma_f32_16x16x32_bf16 v[80:83], v[176:179], v[200:203], 0
	v_mfma_f32_16x16x32_bf16 v[68:71], v[168:171], v[208:211], 0
	v_mfma_f32_16x16x32_bf16 v[64:67], v[176:179], v[208:211], 0
	v_mfma_f32_16x16x32_bf16 v[116:119], v[172:175], v[188:191], v[116:119]
	v_mfma_f32_16x16x32_bf16 v[112:115], v[180:183], v[188:191], v[112:115]
	v_mfma_f32_16x16x32_bf16 v[100:103], v[172:175], v[196:199], v[100:103]
	v_mfma_f32_16x16x32_bf16 v[96:99], v[180:183], v[196:199], v[96:99]
	v_mfma_f32_16x16x32_bf16 v[84:87], v[172:175], v[204:207], v[84:87]
	v_mfma_f32_16x16x32_bf16 v[80:83], v[180:183], v[204:207], v[80:83]
	v_mfma_f32_16x16x32_bf16 v[68:71], v[172:175], v[214:217], v[68:71]
	v_mfma_f32_16x16x32_bf16 v[64:67], v[180:183], v[214:217], v[64:67]
	s_setprio 0
	s_barrier
	s_add_i32 s44, s44, s2
	s_mov_b32 m0, s44
	ds_read_b128 v[184:187], v167 offset:16384
	ds_read_b128 v[188:191], v167 offset:17408
	ds_read_b128 v[192:195], v167 offset:18432
	ds_read_b128 v[196:199], v167 offset:19456
	ds_read_b128 v[200:203], v167 offset:20480
	ds_read_b128 v[204:207], v167 offset:21504
	ds_read_b128 v[208:211], v167 offset:22528
	ds_read_b128 v[214:217], v167 offset:23552
	global_load_lds_dwordx4 v132, s[26:27]
	s_add_i32 m0, s44, 0x2000
	s_add_u32 s44, s26, 0x40000
	s_addc_u32 s45, s27, 0
	s_add_i32 s46, s46, s2
	global_load_lds_dwordx4 v128, s[26:27]
	s_mov_b32 m0, s46
	s_nop 0
	global_load_lds_dwordx4 v132, s[44:45]
	s_add_i32 m0, s46, 0x2000
	s_nop 0
	global_load_lds_dwordx4 v128, s[44:45]
	s_mov_b32 m0, s52
	s_nop 0
	global_load_lds_dwordx4 v134, s[36:37]
	s_mov_b32 m0, s53
	s_nop 0
	global_load_lds_dwordx4 v130, s[36:37]
	s_waitcnt vmcnt(8)
	s_waitcnt lgkmcnt(0)
	s_barrier
; #define PG8_STAGE(bufoff, gbase, voff) do { _Pragma("unroll") for (int _i = 0; _i < 2; ++_i) \
;         __builtin_amdgcn_global_load_lds((const unsigned*)((const char*)(gbase) + (voff)[_i]), (LAS unsigned*)(lds + (bufoff) + ldsw + _i * 8192), 16, 0, 0); } while (0)
; #define PG8_LDA(dst, b, h) do { _Pragma("unroll") for (int m = 0; m < 4; ++m) _Pragma("unroll") for (int k = 0; k < 2; ++k) dst[m][k] = *(const LAS bf16x8*)(lds + PG8_SA(b, h) + aoff + m * 2048 + k * 1024); } while (0)
; #define PG8_LDB(dst, b, h) do { _Pragma("unroll") for (int n = 0; n < 2; ++n) _Pragma("unroll") for (int k = 0; k < 2; ++k) dst[n][k] = *(const LAS bf16x8*)(lds + PG8_SB(b, h) + boff + n * 2048 + k * 1024); } while (0)
; #define PG8_MMA(ai, bj, At, Bt) do { __builtin_amdgcn_s_setprio(1); _Pragma("unroll") for (int m = 0; m < 4; ++m) _Pragma("unroll") for (int n = 0; n < 2; ++n) _Pragma("unroll") for (int k = 0; k < 2; ++k) \
;         acc[ai][bj][m][n] = __builtin_amdgcn_mfma_f32_16x16x32_bf16(Bt[n][k], At[m][k], acc[ai][bj][m][n], 0, 0, 0); __builtin_amdgcn_s_setprio(0); } while (0)
; #define PG8_WAIT_V(n) asm volatile("s_waitcnt vmcnt(" #n ")" ::: "memory")
; #define PG8_WAIT_L(n) asm volatile("s_waitcnt lgkmcnt(" #n ")" ::: "memory")
; #define PG8_BAR __builtin_amdgcn_s_barrier()
; #define PG8_SCHED __builtin_amdgcn_sched_barrier(0)
; template <class Epi, class Sched>
; __device__ __forceinline__ void gemm_phase(LAS unsigned char* lds, const Gemm g, const Sched& S, const Epi& E) {
;     ...
;             PG8_WAIT_V(8); PG8_WAIT_L(0); PG8_BAR; PG8_MMA(1, 0, At, B0); PG8_MMA(1, 1, At, B1); PG8_BAR; PG8_SCHED;
;             PG8_LDB(B0, 1, 0); PG8_LDB(B1, 1, 1); PG8_SCHED; PG8_LDA(At, 1, 0); PG8_STAGE(PG8_SA(0, 1), a2 + hstepA, voffA);
;             PG8_WAIT_V(8); PG8_WAIT_L(0); PG8_BAR; PG8_MMA(0, 0, At, B0); PG8_MMA(0, 1, At, B1); PG8_BAR; PG8_SCHED;
	s_setprio 1
	s_waitcnt lgkmcnt(0)
	v_mfma_f32_16x16x32_bf16 v[60:63], v[148:151], v[184:187], 0
	v_mfma_f32_16x16x32_bf16 v[56:59], v[156:159], v[184:187], 0
	v_mfma_f32_16x16x32_bf16 v[44:47], v[148:151], v[192:195], 0
	v_mfma_f32_16x16x32_bf16 v[40:43], v[156:159], v[192:195], 0
	v_mfma_f32_16x16x32_bf16 v[28:31], v[148:151], v[200:203], 0
	v_mfma_f32_16x16x32_bf16 v[24:27], v[156:159], v[200:203], 0
	v_mfma_f32_16x16x32_bf16 v[12:15], v[148:151], v[208:211], 0
	v_mfma_f32_16x16x32_bf16 v[8:11], v[156:159], v[208:211], 0
	v_mfma_f32_16x16x32_bf16 v[60:63], v[152:155], v[188:191], v[60:63]
	v_mfma_f32_16x16x32_bf16 v[56:59], v[160:163], v[188:191], v[56:59]
	v_mfma_f32_16x16x32_bf16 v[44:47], v[152:155], v[196:199], v[44:47]
	v_mfma_f32_16x16x32_bf16 v[40:43], v[160:163], v[196:199], v[40:43]
	v_mfma_f32_16x16x32_bf16 v[28:31], v[152:155], v[204:207], v[28:31]
	v_mfma_f32_16x16x32_bf16 v[24:27], v[160:163], v[204:207], v[24:27]
	v_mfma_f32_16x16x32_bf16 v[12:15], v[152:155], v[214:217], v[12:15]
	v_mfma_f32_16x16x32_bf16 v[8:11], v[160:163], v[214:217], v[8:11]
	s_setprio 0
	s_setprio 1
	v_mfma_f32_16x16x32_bf16 v[52:55], v[168:171], v[184:187], 0
	v_mfma_f32_16x16x32_bf16 v[48:51], v[176:179], v[184:187], 0
	v_mfma_f32_16x16x32_bf16 v[36:39], v[168:171], v[192:195], 0
	v_mfma_f32_16x16x32_bf16 v[32:35], v[176:179], v[192:195], 0
	v_mfma_f32_16x16x32_bf16 v[20:23], v[168:171], v[200:203], 0
	v_mfma_f32_16x16x32_bf16 v[16:19], v[176:179], v[200:203], 0
	v_mfma_f32_16x16x32_bf16 v[4:7], v[168:171], v[208:211], 0
	v_mfma_f32_16x16x32_bf16 v[0:3], v[176:179], v[208:211], 0
	v_mfma_f32_16x16x32_bf16 v[52:55], v[172:175], v[188:191], v[52:55]
	v_mfma_f32_16x16x32_bf16 v[48:51], v[180:183], v[188:191], v[48:51]
	v_mfma_f32_16x16x32_bf16 v[36:39], v[172:175], v[196:199], v[36:39]
	v_mfma_f32_16x16x32_bf16 v[32:35], v[180:183], v[196:199], v[32:35]
	v_mfma_f32_16x16x32_bf16 v[20:23], v[172:175], v[204:207], v[20:23]
	v_mfma_f32_16x16x32_bf16 v[16:19], v[180:183], v[204:207], v[16:19]
	v_mfma_f32_16x16x32_bf16 v[4:7], v[172:175], v[214:217], v[4:7]
	v_mfma_f32_16x16x32_bf16 v[0:3], v[180:183], v[214:217], v[0:3]
	s_setprio 0
	s_barrier
	s_add_i32 s44, 0, 0x18000
	v_add_u32_e32 v145, s44, v165
	s_add_i32 s45, 0, 0x1c000
	ds_read_b128 v[148:151], v145
	ds_read_b128 v[152:155], v145 offset:1024
	ds_read_b128 v[156:159], v145 offset:2048
	ds_read_b128 v[160:163], v145 offset:3072
	v_add_u32_e32 v145, s45, v165
	ds_read_b128 v[168:171], v145
	ds_read_b128 v[172:175], v145 offset:1024
	ds_read_b128 v[176:179], v145 offset:2048
	ds_read_b128 v[180:183], v145 offset:3072
	s_add_u32 s36, s36, 0x40000
	s_addc_u32 s37, s37, 0
	s_mov_b32 m0, s54
	ds_read_b128 v[184:187], v167 offset:32768
	ds_read_b128 v[188:191], v167 offset:33792
	ds_read_b128 v[192:195], v167 offset:34816
	ds_read_b128 v[196:199], v167 offset:35840
	ds_read_b128 v[200:203], v167 offset:36864
	ds_read_b128 v[204:207], v167 offset:37888
	ds_read_b128 v[208:211], v167 offset:38912
	ds_read_b128 v[214:217], v167 offset:39936
	global_load_lds_dwordx4 v134, s[36:37]
	s_mov_b32 m0, s55
	s_nop 0
	global_load_lds_dwordx4 v130, s[36:37]
	s_waitcnt vmcnt(8)
	s_waitcnt lgkmcnt(0)
	s_barrier
	s_setprio 1
	s_waitcnt lgkmcnt(0)
	v_mfma_f32_16x16x32_bf16 v[124:127], v[148:151], v[184:187], v[124:127]
	v_mfma_f32_16x16x32_bf16 v[120:123], v[156:159], v[184:187], v[120:123]
	v_mfma_f32_16x16x32_bf16 v[108:111], v[148:151], v[192:195], v[108:111]
	v_mfma_f32_16x16x32_bf16 v[104:107], v[156:159], v[192:195], v[104:107]
	v_mfma_f32_16x16x32_bf16 v[92:95], v[148:151], v[200:203], v[92:95]
	v_mfma_f32_16x16x32_bf16 v[88:91], v[156:159], v[200:203], v[88:91]
	v_mfma_f32_16x16x32_bf16 v[76:79], v[148:151], v[208:211], v[76:79]
	v_mfma_f32_16x16x32_bf16 v[72:75], v[156:159], v[208:211], v[72:75]
	v_mfma_f32_16x16x32_bf16 v[124:127], v[152:155], v[188:191], v[124:127]
	v_mfma_f32_16x16x32_bf16 v[120:123], v[160:163], v[188:191], v[120:123]
	v_mfma_f32_16x16x32_bf16 v[108:111], v[152:155], v[196:199], v[108:111]
	v_mfma_f32_16x16x32_bf16 v[104:107], v[160:163], v[196:199], v[104:107]
	v_mfma_f32_16x16x32_bf16 v[92:95], v[152:155], v[204:207], v[92:95]
	v_mfma_f32_16x16x32_bf16 v[88:91], v[160:163], v[204:207], v[88:91]
	v_mfma_f32_16x16x32_bf16 v[76:79], v[152:155], v[214:217], v[76:79]
	v_mfma_f32_16x16x32_bf16 v[72:75], v[160:163], v[214:217], v[72:75]
	s_setprio 0
	s_setprio 1
	v_mfma_f32_16x16x32_bf16 v[116:119], v[168:171], v[184:187], v[116:119]
	v_mfma_f32_16x16x32_bf16 v[112:115], v[176:179], v[184:187], v[112:115]
	v_mfma_f32_16x16x32_bf16 v[100:103], v[168:171], v[192:195], v[100:103]
	v_mfma_f32_16x16x32_bf16 v[96:99], v[176:179], v[192:195], v[96:99]
	v_mfma_f32_16x16x32_bf16 v[84:87], v[168:171], v[200:203], v[84:87]
	v_mfma_f32_16x16x32_bf16 v[80:83], v[176:179], v[200:203], v[80:83]
	v_mfma_f32_16x16x32_bf16 v[68:71], v[168:171], v[208:211], v[68:71]
	v_mfma_f32_16x16x32_bf16 v[64:67], v[176:179], v[208:211], v[64:67]
	v_mfma_f32_16x16x32_bf16 v[116:119], v[172:175], v[188:191], v[116:119]
	v_mfma_f32_16x16x32_bf16 v[112:115], v[180:183], v[188:191], v[112:115]
	v_mfma_f32_16x16x32_bf16 v[100:103], v[172:175], v[196:199], v[100:103]
	v_mfma_f32_16x16x32_bf16 v[96:99], v[180:183], v[196:199], v[96:99]
	v_mfma_f32_16x16x32_bf16 v[84:87], v[172:175], v[204:207], v[84:87]
	v_mfma_f32_16x16x32_bf16 v[80:83], v[180:183], v[204:207], v[80:83]
	v_mfma_f32_16x16x32_bf16 v[68:71], v[172:175], v[214:217], v[68:71]
	v_mfma_f32_16x16x32_bf16 v[64:67], v[180:183], v[214:217], v[64:67]
	s_setprio 0
	s_barrier
; #define PG8_STAGE(bufoff, gbase, voff) do { _Pragma("unroll") for (int _i = 0; _i < 2; ++_i) \
;         __builtin_amdgcn_global_load_lds((const unsigned*)((const char*)(gbase) + (voff)[_i]), (LAS unsigned*)(lds + (bufoff) + ldsw + _i * 8192), 16, 0, 0); } while (0)
; #define PG8_LDA(dst, b, h) do { _Pragma("unroll") for (int m = 0; m < 4; ++m) _Pragma("unroll") for (int k = 0; k < 2; ++k) dst[m][k] = *(const LAS bf16x8*)(lds + PG8_SA(b, h) + aoff + m * 2048 + k * 1024); } while (0)
; #define PG8_LDB(dst, b, h) do { _Pragma("unroll") for (int n = 0; n < 2; ++n) _Pragma("unroll") for (int k = 0; k < 2; ++k) dst[n][k] = *(const LAS bf16x8*)(lds + PG8_SB(b, h) + boff + n * 2048 + k * 1024); } while (0)
; #define PG8_MMA(ai, bj, At, Bt) do { __builtin_amdgcn_s_setprio(1); _Pragma("unroll") for (int m = 0; m < 4; ++m) _Pragma("unroll") for (int n = 0; n < 2; ++n) _Pragma("unroll") for (int k = 0; k < 2; ++k) \
;         acc[ai][bj][m][n] = __builtin_amdgcn_mfma_f32_16x16x32_bf16(Bt[n][k], At[m][k], acc[ai][bj][m][n], 0, 0, 0); __builtin_amdgcn_s_setprio(0); } while (0)
; #define PG8_WAIT_V(n) asm volatile("s_waitcnt vmcnt(" #n ")" ::: "memory")
; #define PG8_WAIT_L(n) asm volatile("s_waitcnt lgkmcnt(" #n ")" ::: "memory")
; #define PG8_BAR __builtin_amdgcn_s_barrier()
; #define PG8_SCHED __builtin_amdgcn_sched_barrier(0)
; template <class Epi, class Sched>
; __device__ __forceinline__ void gemm_phase(LAS unsigned char* lds, const Gemm g, const Sched& S, const Epi& E) {
;     ...
;         for (int t = 0; t < nt; t += 2) {
;             const bool last = (t == nt - 2);
;             const char* a1 = cA + (size_t)(t + 1) * kstep;
;             const char* a2 = last ? nA : cA + (size_t)(t + 2) * kstep; const char* b2 = last ? nB : cB + (size_t)(t + 2) * kstep;
;             const char* a3 = a2 + kstep; const char* b3 = b2 + kstep;
;             PG8_LDB(B0, 0, 0); PG8_LDB(B1, 0, 1); PG8_SCHED; PG8_LDA(At, 0, 0); PG8_STAGE(PG8_SA(1, 1), a1 + hstepA, voffA);
;     ...
;             PG8_LDA(At, 1, 1); PG8_STAGE(PG8_SB(1, 0), b3, voffB); PG8_STAGE(PG8_SB(1, 1), b3 + hstepB, voffB); PG8_STAGE(PG8_SA(1, 0), a3, voffA);
;             PG8_WAIT_V(8); PG8_WAIT_L(0); PG8_BAR; PG8_MMA(1, 0, At, B0); PG8_MMA(1, 1, At, B1); PG8_BAR; PG8_SCHED;
;         }
	s_add_u32 s98, s36, 0xfffc0080
	s_addc_u32 s99, s37, -1
	s_add_u32 s62, s26, 0x80
	s_addc_u32 s63, s27, 0
	s_add_i32 s36, s44, s2
	s_mov_b32 m0, s36
	ds_read_b128 v[184:187], v167 offset:49152
	ds_read_b128 v[188:191], v167 offset:50176
	ds_read_b128 v[192:195], v167 offset:51200
	ds_read_b128 v[196:199], v167 offset:52224
	ds_read_b128 v[200:203], v167 offset:53248
	ds_read_b128 v[204:207], v167 offset:54272
	ds_read_b128 v[208:211], v167 offset:55296
	ds_read_b128 v[214:217], v167 offset:56320
	global_load_lds_dwordx4 v132, s[62:63]
	s_add_i32 m0, s36, 0x2000
	s_add_u32 s26, s26, 0x40080
	s_addc_u32 s27, s27, 0
	s_add_i32 s36, s45, s2
	global_load_lds_dwordx4 v128, s[62:63]
	s_mov_b32 m0, s36
	s_nop 0
	global_load_lds_dwordx4 v132, s[26:27]
	s_add_i32 m0, s36, 0x2000
	s_nop 0
	global_load_lds_dwordx4 v128, s[26:27]
	s_mov_b32 m0, s56
	s_nop 0
	global_load_lds_dwordx4 v134, s[98:99]
	s_mov_b32 m0, s57
	s_nop 0
	global_load_lds_dwordx4 v130, s[98:99]
	s_waitcnt vmcnt(8)
	s_waitcnt lgkmcnt(0)
	s_barrier
	s_setprio 1
	s_waitcnt lgkmcnt(0)
	v_mfma_f32_16x16x32_bf16 v[60:63], v[148:151], v[184:187], v[60:63]
	v_mfma_f32_16x16x32_bf16 v[56:59], v[156:159], v[184:187], v[56:59]
	v_mfma_f32_16x16x32_bf16 v[44:47], v[148:151], v[192:195], v[44:47]
	v_mfma_f32_16x16x32_bf16 v[40:43], v[156:159], v[192:195], v[40:43]
	v_mfma_f32_16x16x32_bf16 v[28:31], v[148:151], v[200:203], v[28:31]
	v_mfma_f32_16x16x32_bf16 v[24:27], v[156:159], v[200:203], v[24:27]
	v_mfma_f32_16x16x32_bf16 v[12:15], v[148:151], v[208:211], v[12:15]
	v_mfma_f32_16x16x32_bf16 v[8:11], v[156:159], v[208:211], v[8:11]
	v_mfma_f32_16x16x32_bf16 v[60:63], v[152:155], v[188:191], v[60:63]
	v_mfma_f32_16x16x32_bf16 v[56:59], v[160:163], v[188:191], v[56:59]
	v_mfma_f32_16x16x32_bf16 v[44:47], v[152:155], v[196:199], v[44:47]
	v_mfma_f32_16x16x32_bf16 v[40:43], v[160:163], v[196:199], v[40:43]
	v_mfma_f32_16x16x32_bf16 v[28:31], v[152:155], v[204:207], v[28:31]
	v_mfma_f32_16x16x32_bf16 v[24:27], v[160:163], v[204:207], v[24:27]
	v_mfma_f32_16x16x32_bf16 v[12:15], v[152:155], v[214:217], v[12:15]
	v_mfma_f32_16x16x32_bf16 v[8:11], v[160:163], v[214:217], v[8:11]
	s_setprio 0
	s_setprio 1
	v_mfma_f32_16x16x32_bf16 v[52:55], v[168:171], v[184:187], v[52:55]
	v_mfma_f32_16x16x32_bf16 v[48:51], v[176:179], v[184:187], v[48:51]
	v_mfma_f32_16x16x32_bf16 v[36:39], v[168:171], v[192:195], v[36:39]
	v_mfma_f32_16x16x32_bf16 v[32:35], v[176:179], v[192:195], v[32:35]
	v_mfma_f32_16x16x32_bf16 v[20:23], v[168:171], v[200:203], v[20:23]
	v_mfma_f32_16x16x32_bf16 v[16:19], v[176:179], v[200:203], v[16:19]
	v_mfma_f32_16x16x32_bf16 v[4:7], v[168:171], v[208:211], v[4:7]
	v_mfma_f32_16x16x32_bf16 v[0:3], v[176:179], v[208:211], v[0:3]
	v_mfma_f32_16x16x32_bf16 v[52:55], v[172:175], v[188:191], v[52:55]
	v_mfma_f32_16x16x32_bf16 v[48:51], v[180:183], v[188:191], v[48:51]
	v_mfma_f32_16x16x32_bf16 v[36:39], v[172:175], v[196:199], v[36:39]
	v_mfma_f32_16x16x32_bf16 v[32:35], v[180:183], v[196:199], v[32:35]
	v_mfma_f32_16x16x32_bf16 v[20:23], v[172:175], v[204:207], v[20:23]
	v_mfma_f32_16x16x32_bf16 v[16:19], v[180:183], v[204:207], v[16:19]
	v_mfma_f32_16x16x32_bf16 v[4:7], v[172:175], v[214:217], v[4:7]
	v_mfma_f32_16x16x32_bf16 v[0:3], v[180:183], v[214:217], v[0:3]
	s_setprio 0
	s_barrier
	s_add_i32 s43, s43, 2
	s_add_u32 s24, s24, 0x100
	s_addc_u32 s25, s25, 0
	s_add_u32 s19, s19, 0x100
	s_addc_u32 s42, s42, 0
.LBB0_280:
	s_add_u32 s26, s24, 0xfffc0080
	s_addc_u32 s27, s25, -1
	s_add_i32 s44, 0, 0x10000
	s_cmp_eq_u32 s43, 12
	s_cselect_b32 s37, s6, s27
	s_cselect_b32 s36, s14, s26
	v_add_u32_e32 v145, s44, v165
	s_cselect_b32 s27, s15, s42
	s_cselect_b32 s26, s17, s19
	s_add_i32 s46, 0, 0x14000
	ds_read_b128 v[148:151], v145
	ds_read_b128 v[152:155], v145 offset:1024
	ds_read_b128 v[156:159], v145 offset:2048
	ds_read_b128 v[160:163], v145 offset:3072
	v_add_u32_e32 v145, s46, v165
	ds_read_b128 v[168:171], v145
	ds_read_b128 v[172:175], v145 offset:1024
	ds_read_b128 v[176:179], v145 offset:2048
	ds_read_b128 v[180:183], v145 offset:3072
	s_add_i32 m0, s52, 0xc000
	ds_read_b128 v[184:187], v167
	ds_read_b128 v[188:191], v167 offset:1024
	ds_read_b128 v[192:195], v167 offset:2048
	ds_read_b128 v[196:199], v167 offset:3072
	ds_read_b128 v[200:203], v167 offset:4096
	ds_read_b128 v[204:207], v167 offset:5120
	ds_read_b128 v[208:211], v167 offset:6144
	ds_read_b128 v[214:217], v167 offset:7168
	global_load_lds_dwordx4 v140, s[24:25]
	s_add_i32 m0, s52, 0xe000
	s_nop 0
	global_load_lds_dwordx4 v142, s[24:25]
	s_waitcnt vmcnt(8)
	s_waitcnt lgkmcnt(0)
	s_barrier
; #define PG8_STAGE(bufoff, gbase, voff) do { _Pragma("unroll") for (int _i = 0; _i < 2; ++_i) \
;         __builtin_amdgcn_global_load_lds((const unsigned*)((const char*)(gbase) + (voff)[_i]), (LAS unsigned*)(lds + (bufoff) + ldsw + _i * 8192), 16, 0, 0); } while (0)
; #define PG8_LDA(dst, b, h) do { _Pragma("unroll") for (int m = 0; m < 4; ++m) _Pragma("unroll") for (int k = 0; k < 2; ++k) dst[m][k] = *(const LAS bf16x8*)(lds + PG8_SA(b, h) + aoff + m * 2048 + k * 1024); } while (0)
; #define PG8_LDB(dst, b, h) do { _Pragma("unroll") for (int n = 0; n < 2; ++n) _Pragma("unroll") for (int k = 0; k < 2; ++k) dst[n][k] = *(const LAS bf16x8*)(lds + PG8_SB(b, h) + boff + n * 2048 + k * 1024); } while (0)
; #define PG8_MMA(ai, bj, At, Bt) do { __builtin_amdgcn_s_setprio(1); _Pragma("unroll") for (int m = 0; m < 4; ++m) _Pragma("unroll") for (int n = 0; n < 2; ++n) _Pragma("unroll") for (int k = 0; k < 2; ++k) \
;         acc[ai][bj][m][n] = __builtin_amdgcn_mfma_f32_16x16x32_bf16(Bt[n][k], At[m][k], acc[ai][bj][m][n], 0, 0, 0); __builtin_amdgcn_s_setprio(0); } while (0)
; #define PG8_WAIT_V(n) asm volatile("s_waitcnt vmcnt(" #n ")" ::: "memory")
; #define PG8_WAIT_L(n) asm volatile("s_waitcnt lgkmcnt(" #n ")" ::: "memory")
; #define PG8_BAR __builtin_amdgcn_s_barrier()
; #define PG8_SCHED __builtin_amdgcn_sched_barrier(0)
; template <class Epi, class Sched>
; __device__ __forceinline__ void gemm_phase(LAS unsigned char* lds, const Gemm g, const Sched& S, const Epi& E) {
;     ...
;             PG8_LDB(B0, 0, 0); PG8_LDB(B1, 0, 1); PG8_SCHED; PG8_LDA(At, 0, 0); PG8_STAGE(PG8_SA(1, 1), a1 + hstepA, voffA);
;             PG8_WAIT_V(8); PG8_WAIT_L(0); PG8_BAR; PG8_MMA(0, 0, At, B0); PG8_MMA(0, 1, At, B1); PG8_BAR; PG8_SCHED;
;             PG8_LDA(At, 0, 1); PG8_STAGE(PG8_SB(0, 0), b2, voffB); PG8_STAGE(PG8_SB(0, 1), b2 + hstepB, voffB); PG8_STAGE(PG8_SA(0, 0), a2, voffA);
;             PG8_WAIT_V(8); PG8_WAIT_L(0); PG8_BAR; PG8_MMA(1, 0, At, B0); PG8_MMA(1, 1, At, B1); PG8_BAR; PG8_SCHED;
	s_setprio 1
	s_waitcnt lgkmcnt(0)
	v_mfma_f32_16x16x32_bf16 v[124:127], v[148:151], v[184:187], v[124:127]
	v_mfma_f32_16x16x32_bf16 v[120:123], v[156:159], v[184:187], v[120:123]
	v_mfma_f32_16x16x32_bf16 v[108:111], v[148:151], v[192:195], v[108:111]
	v_mfma_f32_16x16x32_bf16 v[104:107], v[156:159], v[192:195], v[104:107]
	v_mfma_f32_16x16x32_bf16 v[92:95], v[148:151], v[200:203], v[92:95]
	v_mfma_f32_16x16x32_bf16 v[88:91], v[156:159], v[200:203], v[88:91]
	v_mfma_f32_16x16x32_bf16 v[76:79], v[148:151], v[208:211], v[76:79]
	v_mfma_f32_16x16x32_bf16 v[72:75], v[156:159], v[208:211], v[72:75]
	v_mfma_f32_16x16x32_bf16 v[124:127], v[152:155], v[188:191], v[124:127]
	v_mfma_f32_16x16x32_bf16 v[120:123], v[160:163], v[188:191], v[120:123]
	v_mfma_f32_16x16x32_bf16 v[108:111], v[152:155], v[196:199], v[108:111]
	v_mfma_f32_16x16x32_bf16 v[104:107], v[160:163], v[196:199], v[104:107]
	v_mfma_f32_16x16x32_bf16 v[92:95], v[152:155], v[204:207], v[92:95]
	v_mfma_f32_16x16x32_bf16 v[88:91], v[160:163], v[204:207], v[88:91]
	v_mfma_f32_16x16x32_bf16 v[76:79], v[152:155], v[214:217], v[76:79]
	v_mfma_f32_16x16x32_bf16 v[72:75], v[160:163], v[214:217], v[72:75]
	s_setprio 0
	s_setprio 1
	v_mfma_f32_16x16x32_bf16 v[116:119], v[168:171], v[184:187], v[116:119]
	v_mfma_f32_16x16x32_bf16 v[112:115], v[176:179], v[184:187], v[112:115]
	v_mfma_f32_16x16x32_bf16 v[100:103], v[168:171], v[192:195], v[100:103]
	v_mfma_f32_16x16x32_bf16 v[96:99], v[176:179], v[192:195], v[96:99]
	v_mfma_f32_16x16x32_bf16 v[84:87], v[168:171], v[200:203], v[84:87]
	v_mfma_f32_16x16x32_bf16 v[80:83], v[176:179], v[200:203], v[80:83]
	v_mfma_f32_16x16x32_bf16 v[68:71], v[168:171], v[208:211], v[68:71]
	v_mfma_f32_16x16x32_bf16 v[64:67], v[176:179], v[208:211], v[64:67]
	v_mfma_f32_16x16x32_bf16 v[116:119], v[172:175], v[188:191], v[116:119]
	v_mfma_f32_16x16x32_bf16 v[112:115], v[180:183], v[188:191], v[112:115]
	v_mfma_f32_16x16x32_bf16 v[100:103], v[172:175], v[196:199], v[100:103]
	v_mfma_f32_16x16x32_bf16 v[96:99], v[180:183], v[196:199], v[96:99]
	v_mfma_f32_16x16x32_bf16 v[84:87], v[172:175], v[204:207], v[84:87]
	v_mfma_f32_16x16x32_bf16 v[80:83], v[180:183], v[204:207], v[80:83]
	v_mfma_f32_16x16x32_bf16 v[68:71], v[172:175], v[214:217], v[68:71]
	v_mfma_f32_16x16x32_bf16 v[64:67], v[180:183], v[214:217], v[64:67]
	s_setprio 0
	s_barrier
	s_add_i32 s44, s44, s2
	s_mov_b32 m0, s44
	ds_read_b128 v[184:187], v167 offset:16384
	ds_read_b128 v[188:191], v167 offset:17408
	ds_read_b128 v[192:195], v167 offset:18432
	ds_read_b128 v[196:199], v167 offset:19456
	ds_read_b128 v[200:203], v167 offset:20480
	ds_read_b128 v[204:207], v167 offset:21504
	ds_read_b128 v[208:211], v167 offset:22528
	ds_read_b128 v[214:217], v167 offset:23552
	global_load_lds_dwordx4 v132, s[26:27]
	s_add_i32 m0, s44, 0x2000
	s_add_u32 s44, s26, 0x40000
	s_addc_u32 s45, s27, 0
	s_add_i32 s46, s46, s2
	global_load_lds_dwordx4 v128, s[26:27]
	s_mov_b32 m0, s46
	s_nop 0
	global_load_lds_dwordx4 v132, s[44:45]
	s_add_i32 m0, s46, 0x2000
	s_nop 0
	global_load_lds_dwordx4 v128, s[44:45]
	s_mov_b32 m0, s52
	s_nop 0
	global_load_lds_dwordx4 v134, s[36:37]
	s_mov_b32 m0, s53
	s_nop 0
	global_load_lds_dwordx4 v130, s[36:37]
	s_waitcnt vmcnt(8)
	s_waitcnt lgkmcnt(0)
	s_barrier
	s_setprio 1
	s_waitcnt lgkmcnt(0)
	v_mfma_f32_16x16x32_bf16 v[60:63], v[148:151], v[184:187], v[60:63]
	v_mfma_f32_16x16x32_bf16 v[56:59], v[156:159], v[184:187], v[56:59]
	v_mfma_f32_16x16x32_bf16 v[44:47], v[148:151], v[192:195], v[44:47]
	v_mfma_f32_16x16x32_bf16 v[40:43], v[156:159], v[192:195], v[40:43]
	v_mfma_f32_16x16x32_bf16 v[28:31], v[148:151], v[200:203], v[28:31]
	v_mfma_f32_16x16x32_bf16 v[24:27], v[156:159], v[200:203], v[24:27]
	v_mfma_f32_16x16x32_bf16 v[12:15], v[148:151], v[208:211], v[12:15]
	v_mfma_f32_16x16x32_bf16 v[8:11], v[156:159], v[208:211], v[8:11]
	v_mfma_f32_16x16x32_bf16 v[60:63], v[152:155], v[188:191], v[60:63]
	v_mfma_f32_16x16x32_bf16 v[56:59], v[160:163], v[188:191], v[56:59]
	v_mfma_f32_16x16x32_bf16 v[44:47], v[152:155], v[196:199], v[44:47]
	v_mfma_f32_16x16x32_bf16 v[40:43], v[160:163], v[196:199], v[40:43]
	v_mfma_f32_16x16x32_bf16 v[28:31], v[152:155], v[204:207], v[28:31]
	v_mfma_f32_16x16x32_bf16 v[24:27], v[160:163], v[204:207], v[24:27]
	v_mfma_f32_16x16x32_bf16 v[12:15], v[152:155], v[214:217], v[12:15]
	v_mfma_f32_16x16x32_bf16 v[8:11], v[160:163], v[214:217], v[8:11]
	s_setprio 0
	s_setprio 1
	v_mfma_f32_16x16x32_bf16 v[52:55], v[168:171], v[184:187], v[52:55]
	v_mfma_f32_16x16x32_bf16 v[48:51], v[176:179], v[184:187], v[48:51]
	v_mfma_f32_16x16x32_bf16 v[36:39], v[168:171], v[192:195], v[36:39]
	v_mfma_f32_16x16x32_bf16 v[32:35], v[176:179], v[192:195], v[32:35]
	v_mfma_f32_16x16x32_bf16 v[20:23], v[168:171], v[200:203], v[20:23]
	v_mfma_f32_16x16x32_bf16 v[16:19], v[176:179], v[200:203], v[16:19]
	v_mfma_f32_16x16x32_bf16 v[4:7], v[168:171], v[208:211], v[4:7]
	v_mfma_f32_16x16x32_bf16 v[0:3], v[176:179], v[208:211], v[0:3]
	v_mfma_f32_16x16x32_bf16 v[52:55], v[172:175], v[188:191], v[52:55]
	v_mfma_f32_16x16x32_bf16 v[48:51], v[180:183], v[188:191], v[48:51]
	v_mfma_f32_16x16x32_bf16 v[36:39], v[172:175], v[196:199], v[36:39]
	v_mfma_f32_16x16x32_bf16 v[32:35], v[180:183], v[196:199], v[32:35]
	v_mfma_f32_16x16x32_bf16 v[20:23], v[172:175], v[204:207], v[20:23]
	v_mfma_f32_16x16x32_bf16 v[16:19], v[180:183], v[204:207], v[16:19]
	v_mfma_f32_16x16x32_bf16 v[4:7], v[172:175], v[214:217], v[4:7]
	v_mfma_f32_16x16x32_bf16 v[0:3], v[180:183], v[214:217], v[0:3]
	s_setprio 0
	s_barrier
; #define PG8_STAGE(bufoff, gbase, voff) do { _Pragma("unroll") for (int _i = 0; _i < 2; ++_i) \
;         __builtin_amdgcn_global_load_lds((const unsigned*)((const char*)(gbase) + (voff)[_i]), (LAS unsigned*)(lds + (bufoff) + ldsw + _i * 8192), 16, 0, 0); } while (0)
; #define PG8_LDA(dst, b, h) do { _Pragma("unroll") for (int m = 0; m < 4; ++m) _Pragma("unroll") for (int k = 0; k < 2; ++k) dst[m][k] = *(const LAS bf16x8*)(lds + PG8_SA(b, h) + aoff + m * 2048 + k * 1024); } while (0)
; #define PG8_LDB(dst, b, h) do { _Pragma("unroll") for (int n = 0; n < 2; ++n) _Pragma("unroll") for (int k = 0; k < 2; ++k) dst[n][k] = *(const LAS bf16x8*)(lds + PG8_SB(b, h) + boff + n * 2048 + k * 1024); } while (0)
; #define PG8_MMA(ai, bj, At, Bt) do { __builtin_amdgcn_s_setprio(1); _Pragma("unroll") for (int m = 0; m < 4; ++m) _Pragma("unroll") for (int n = 0; n < 2; ++n) _Pragma("unroll") for (int k = 0; k < 2; ++k) \
;         acc[ai][bj][m][n] = __builtin_amdgcn_mfma_f32_16x16x32_bf16(Bt[n][k], At[m][k], acc[ai][bj][m][n], 0, 0, 0); __builtin_amdgcn_s_setprio(0); } while (0)
; #define PG8_WAIT_V(n) asm volatile("s_waitcnt vmcnt(" #n ")" ::: "memory")
; #define PG8_WAIT_L(n) asm volatile("s_waitcnt lgkmcnt(" #n ")" ::: "memory")
; #define PG8_BAR __builtin_amdgcn_s_barrier()
; #define PG8_SCHED __builtin_amdgcn_sched_barrier(0)
; template <class Epi, class Sched>
; __device__ __forceinline__ void gemm_phase(LAS unsigned char* lds, const Gemm g, const Sched& S, const Epi& E) {
;     ...
;             PG8_LDB(B0, 1, 0); PG8_LDB(B1, 1, 1); PG8_SCHED; PG8_LDA(At, 1, 0); PG8_STAGE(PG8_SA(0, 1), a2 + hstepA, voffA);
;             PG8_WAIT_V(8); PG8_WAIT_L(0); PG8_BAR; PG8_MMA(0, 0, At, B0); PG8_MMA(0, 1, At, B1); PG8_BAR; PG8_SCHED;
;             PG8_LDA(At, 1, 1); PG8_STAGE(PG8_SB(1, 0), b3, voffB); PG8_STAGE(PG8_SB(1, 1), b3 + hstepB, voffB); PG8_STAGE(PG8_SA(1, 0), a3, voffA);
;             PG8_WAIT_V(8); PG8_WAIT_L(0); PG8_BAR; PG8_MMA(1, 0, At, B0); PG8_MMA(1, 1, At, B1); PG8_BAR; PG8_SCHED;
;         }
;         if (wr == 0) PG8_BAR;
	s_add_i32 s44, 0, 0x18000
	v_add_u32_e32 v145, s44, v165
	s_add_i32 s45, 0, 0x1c000
	ds_read_b128 v[148:151], v145
	ds_read_b128 v[152:155], v145 offset:1024
	ds_read_b128 v[156:159], v145 offset:2048
	ds_read_b128 v[160:163], v145 offset:3072
	v_add_u32_e32 v145, s45, v165
	ds_read_b128 v[168:171], v145
	ds_read_b128 v[172:175], v145 offset:1024
	ds_read_b128 v[176:179], v145 offset:2048
	ds_read_b128 v[180:183], v145 offset:3072
	s_add_u32 s36, s36, 0x40000
	s_addc_u32 s37, s37, 0
	s_mov_b32 m0, s54
	ds_read_b128 v[184:187], v167 offset:32768
	ds_read_b128 v[188:191], v167 offset:33792
	ds_read_b128 v[192:195], v167 offset:34816
	ds_read_b128 v[196:199], v167 offset:35840
	ds_read_b128 v[200:203], v167 offset:36864
	ds_read_b128 v[204:207], v167 offset:37888
	ds_read_b128 v[208:211], v167 offset:38912
	ds_read_b128 v[214:217], v167 offset:39936
	global_load_lds_dwordx4 v134, s[36:37]
	s_mov_b32 m0, s55
	s_nop 0
	global_load_lds_dwordx4 v130, s[36:37]
	s_waitcnt vmcnt(8)
	s_waitcnt lgkmcnt(0)
	s_barrier
	s_setprio 1
	s_waitcnt lgkmcnt(0)
	v_mfma_f32_16x16x32_bf16 v[124:127], v[148:151], v[184:187], v[124:127]
	v_mfma_f32_16x16x32_bf16 v[120:123], v[156:159], v[184:187], v[120:123]
	v_mfma_f32_16x16x32_bf16 v[108:111], v[148:151], v[192:195], v[108:111]
	v_mfma_f32_16x16x32_bf16 v[104:107], v[156:159], v[192:195], v[104:107]
	v_mfma_f32_16x16x32_bf16 v[92:95], v[148:151], v[200:203], v[92:95]
	v_mfma_f32_16x16x32_bf16 v[88:91], v[156:159], v[200:203], v[88:91]
	v_mfma_f32_16x16x32_bf16 v[76:79], v[148:151], v[208:211], v[76:79]
	v_mfma_f32_16x16x32_bf16 v[72:75], v[156:159], v[208:211], v[72:75]
	v_mfma_f32_16x16x32_bf16 v[124:127], v[152:155], v[188:191], v[124:127]
	v_mfma_f32_16x16x32_bf16 v[120:123], v[160:163], v[188:191], v[120:123]
	v_mfma_f32_16x16x32_bf16 v[108:111], v[152:155], v[196:199], v[108:111]
	v_mfma_f32_16x16x32_bf16 v[104:107], v[160:163], v[196:199], v[104:107]
	v_mfma_f32_16x16x32_bf16 v[92:95], v[152:155], v[204:207], v[92:95]
	v_mfma_f32_16x16x32_bf16 v[88:91], v[160:163], v[204:207], v[88:91]
	v_mfma_f32_16x16x32_bf16 v[76:79], v[152:155], v[214:217], v[76:79]
	v_mfma_f32_16x16x32_bf16 v[72:75], v[160:163], v[214:217], v[72:75]
	s_setprio 0
	s_setprio 1
	v_mfma_f32_16x16x32_bf16 v[116:119], v[168:171], v[184:187], v[116:119]
	v_mfma_f32_16x16x32_bf16 v[112:115], v[176:179], v[184:187], v[112:115]
	v_mfma_f32_16x16x32_bf16 v[100:103], v[168:171], v[192:195], v[100:103]
	v_mfma_f32_16x16x32_bf16 v[96:99], v[176:179], v[192:195], v[96:99]
	v_mfma_f32_16x16x32_bf16 v[84:87], v[168:171], v[200:203], v[84:87]
	v_mfma_f32_16x16x32_bf16 v[80:83], v[176:179], v[200:203], v[80:83]
	v_mfma_f32_16x16x32_bf16 v[68:71], v[168:171], v[208:211], v[68:71]
	v_mfma_f32_16x16x32_bf16 v[64:67], v[176:179], v[208:211], v[64:67]
	v_mfma_f32_16x16x32_bf16 v[116:119], v[172:175], v[188:191], v[116:119]
	v_mfma_f32_16x16x32_bf16 v[112:115], v[180:183], v[188:191], v[112:115]
	v_mfma_f32_16x16x32_bf16 v[100:103], v[172:175], v[196:199], v[100:103]
	v_mfma_f32_16x16x32_bf16 v[96:99], v[180:183], v[196:199], v[96:99]
	v_mfma_f32_16x16x32_bf16 v[84:87], v[172:175], v[204:207], v[84:87]
	v_mfma_f32_16x16x32_bf16 v[80:83], v[180:183], v[204:207], v[80:83]
	v_mfma_f32_16x16x32_bf16 v[68:71], v[172:175], v[214:217], v[68:71]
	v_mfma_f32_16x16x32_bf16 v[64:67], v[180:183], v[214:217], v[64:67]
	s_setprio 0
	s_barrier
	s_add_u32 s98, s36, 0xfffc0080
	s_addc_u32 s99, s37, -1
	s_add_u32 s62, s26, 0x80
	s_addc_u32 s63, s27, 0
	s_add_i32 s36, s44, s2
	s_mov_b32 m0, s36
	ds_read_b128 v[184:187], v167 offset:49152
	ds_read_b128 v[188:191], v167 offset:50176
	ds_read_b128 v[192:195], v167 offset:51200
	ds_read_b128 v[196:199], v167 offset:52224
	ds_read_b128 v[200:203], v167 offset:53248
	ds_read_b128 v[204:207], v167 offset:54272
	ds_read_b128 v[208:211], v167 offset:55296
	ds_read_b128 v[214:217], v167 offset:56320
	global_load_lds_dwordx4 v132, s[62:63]
	s_add_i32 m0, s36, 0x2000
	s_add_u32 s26, s26, 0x40080
	s_addc_u32 s27, s27, 0
	s_add_i32 s36, s45, s2
	global_load_lds_dwordx4 v128, s[62:63]
	s_mov_b32 m0, s36
	s_nop 0
	global_load_lds_dwordx4 v132, s[26:27]
	s_add_i32 m0, s36, 0x2000
	s_nop 0
	global_load_lds_dwordx4 v128, s[26:27]
	s_mov_b32 m0, s56
	s_nop 0
	global_load_lds_dwordx4 v134, s[98:99]
	s_mov_b32 m0, s57
	s_nop 0
	global_load_lds_dwordx4 v130, s[98:99]
	s_waitcnt vmcnt(8)
	s_waitcnt lgkmcnt(0)
	s_barrier
	s_setprio 1
	s_waitcnt lgkmcnt(0)
	v_mfma_f32_16x16x32_bf16 v[60:63], v[148:151], v[184:187], v[60:63]
	v_mfma_f32_16x16x32_bf16 v[56:59], v[156:159], v[184:187], v[56:59]
	v_mfma_f32_16x16x32_bf16 v[44:47], v[148:151], v[192:195], v[44:47]
	v_mfma_f32_16x16x32_bf16 v[40:43], v[156:159], v[192:195], v[40:43]
	v_mfma_f32_16x16x32_bf16 v[28:31], v[148:151], v[200:203], v[28:31]
	v_mfma_f32_16x16x32_bf16 v[24:27], v[156:159], v[200:203], v[24:27]
	v_mfma_f32_16x16x32_bf16 v[12:15], v[148:151], v[208:211], v[12:15]
	v_mfma_f32_16x16x32_bf16 v[8:11], v[156:159], v[208:211], v[8:11]
	v_mfma_f32_16x16x32_bf16 v[60:63], v[152:155], v[188:191], v[60:63]
	v_mfma_f32_16x16x32_bf16 v[56:59], v[160:163], v[188:191], v[56:59]
	v_mfma_f32_16x16x32_bf16 v[44:47], v[152:155], v[196:199], v[44:47]
	v_mfma_f32_16x16x32_bf16 v[40:43], v[160:163], v[196:199], v[40:43]
	v_mfma_f32_16x16x32_bf16 v[28:31], v[152:155], v[204:207], v[28:31]
	v_mfma_f32_16x16x32_bf16 v[24:27], v[160:163], v[204:207], v[24:27]
	v_mfma_f32_16x16x32_bf16 v[12:15], v[152:155], v[214:217], v[12:15]
	v_mfma_f32_16x16x32_bf16 v[8:11], v[160:163], v[214:217], v[8:11]
	s_setprio 0
	s_setprio 1
	v_mfma_f32_16x16x32_bf16 v[52:55], v[168:171], v[184:187], v[52:55]
	v_mfma_f32_16x16x32_bf16 v[48:51], v[176:179], v[184:187], v[48:51]
	v_mfma_f32_16x16x32_bf16 v[36:39], v[168:171], v[192:195], v[36:39]
	v_mfma_f32_16x16x32_bf16 v[32:35], v[176:179], v[192:195], v[32:35]
	v_mfma_f32_16x16x32_bf16 v[20:23], v[168:171], v[200:203], v[20:23]
	v_mfma_f32_16x16x32_bf16 v[16:19], v[176:179], v[200:203], v[16:19]
	v_mfma_f32_16x16x32_bf16 v[4:7], v[168:171], v[208:211], v[4:7]
	v_mfma_f32_16x16x32_bf16 v[0:3], v[176:179], v[208:211], v[0:3]
	v_mfma_f32_16x16x32_bf16 v[52:55], v[172:175], v[188:191], v[52:55]
	v_mfma_f32_16x16x32_bf16 v[48:51], v[180:183], v[188:191], v[48:51]
	v_mfma_f32_16x16x32_bf16 v[36:39], v[172:175], v[196:199], v[36:39]
	v_mfma_f32_16x16x32_bf16 v[32:35], v[180:183], v[196:199], v[32:35]
	v_mfma_f32_16x16x32_bf16 v[20:23], v[172:175], v[204:207], v[20:23]
	v_mfma_f32_16x16x32_bf16 v[16:19], v[180:183], v[204:207], v[16:19]
	v_mfma_f32_16x16x32_bf16 v[4:7], v[172:175], v[214:217], v[4:7]
	v_mfma_f32_16x16x32_bf16 v[0:3], v[180:183], v[214:217], v[0:3]
	s_setprio 0
	s_barrier
	s_add_i32 s43, s43, 2
	s_add_u32 s24, s24, 0x100
	s_addc_u32 s25, s25, 0
	s_add_u32 s19, s19, 0x100
	s_addc_u32 s42, s42, 0
	s_cmp_gt_u32 s43, 13
	s_cbranch_scc0 .LBB0_280
	s_and_b64 vcc, exec, s[4:5]
	s_cbranch_vccz .LBB0_283
	s_barrier
